# speedup vs baseline: 1.0084x; 1.0084x over previous
; __device__ __forceinline__ int ltid() { int t = threadIdx.x; asm volatile("" : "+v"(t)); return t; }
; __device__ __forceinline__ void phase_attn(const Params& p, const Grp& g, int l) {
;     ...
;   const int S = 1 << g.lgS, nqb = S >> 7, nitems = g.nb * nqb * 8;
;   int par = 0;
;   const int tid = ltid(), w = tid >> 6, lane = tid & 63, fr = lane & 15, fq = lane >> 4;
;   const int qrow0 = w * 16;
;   const int lrow = tid >> 4, lcc = tid & 15;
;   const int ipx = nitems >> 3;
;   const int xq = blockIdx.x & 7, jq = blockIdx.x >> 3;
;   int slot, sstride, send;
;   if (g.type == 1 && gridDim.x == 256) {
;     if (jq == 0) { slot = 0; sstride = 1; send = 7; } else { slot = 7 + (jq - 1); sstride = 31; send = ipx; }
;   } else { slot = jq; sstride = gridDim.x >> 3; send = ipx; }
;   if (slot >= send) return;
;   int item = xq * ipx + slot;
;   int bl = __builtin_amdgcn_readfirstlane(item / (nqb * 8)), rem = item - bl * (nqb * 8), qb = rem >> 3, h = rem & 7;
;   int kb = max(qb - 1, 0);
.LBB0_724:
	v_readlane_b32 s0, v254, 40
	s_and_b32 s4, s0, -2
	s_cmp_eq_u32 s4, 2
	s_load_dwordx2 s[68:69], s[70:71], 0x28
	v_writelane_b32 v254, s70, 36
	s_load_dwordx2 s[8:9], s[70:71], 0x58
	s_cselect_b64 s[12:13], -1, 0
	s_and_b64 vcc, s[12:13], exec
	s_cselect_b32 s40, 14, 11
	s_cselect_b32 s4, 1, 32
	s_add_i32 s14, s40, -7
	v_writelane_b32 v254, s71, 37
	s_lshl_b32 s41, s4, s14
	v_mov_b32_e32 v33, v190
	v_writelane_b32 v254, s0, 40
	s_cbranch_vccnz .LBB0_728
	v_readlane_b32 s0, v254, 1
	v_readlane_b32 s1, v254, 2
	s_load_dword s4, s[0:1], 0x10
	v_readlane_b32 s0, v254, 3
	s_waitcnt lgkmcnt(0)
	s_lshr_b32 s4, s4, 16
	s_cmp_lg_u32 s4, 0
	s_cselect_b64 s[4:5], -1, 0
	s_cmp_lg_u64 s[4:5], 0
	s_addc_u32 s4, s0, 0
	s_cmpk_lg_i32 s4, 0x100
	s_cselect_b64 s[6:7], -1, 0
	s_and_b64 s[4:5], s[6:7], exec
	v_readlane_b32 s0, v254, 22
	s_cselect_b32 s58, s0, 1
	v_readlane_b32 s0, v254, 20
	s_cselect_b32 s59, s0, 0
	v_readlane_b32 s0, v254, 18
	v_readlane_b32 s1, v254, 19
	s_cselect_b32 s4, s41, 5
	s_or_b64 s[6:7], s[6:7], s[0:1]
	s_and_b64 vcc, exec, s[6:7]
	s_cbranch_vccnz .LBB0_727
	v_readlane_b32 s59, v254, 21
	s_nop 3
	s_add_i32 s59, s59, -7
	s_mul_i32 s4, s59, 11
	s_mul_i32 s4, s4, 2115
	s_lshr_b32 s4, s4, 16
	s_lshl_b32 s58, s59, 4
	s_add_i32 s58, s58, s4
	s_add_i32 s59, s59, 1
	s_mul_i32 s4, s59, 11
	s_mul_i32 s4, s4, 2115
	s_lshr_b32 s4, s4, 16
	s_lshl_b32 s59, s59, 4
	s_add_i32 s4, s59, s4
	s_add_i32 s4, s4, 5
	s_add_i32 s59, s58, 5
	s_mov_b32 s58, 1

; __device__ __forceinline__ void phase_attn(const Params& p, const Grp& g, int l) {
;     ...
;   const int xq = blockIdx.x & 7, jq = blockIdx.x >> 3;
;   int slot, sstride, send;
;   if (g.type == 1 && gridDim.x == 256) {
;     if (jq == 0) { slot = 0; sstride = 1; send = 7; } else { slot = 7 + (jq - 1); sstride = 31; send = ipx; }
;   } else { slot = jq; sstride = gridDim.x >> 3; send = ipx; }
;   if (slot >= send) return;
;   int item = xq * ipx + slot;
;   int bl = __builtin_amdgcn_readfirstlane(item / (nqb * 8)), rem = item - bl * (nqb * 8), qb = rem >> 3, h = rem & 7;
;   int kb = max(qb - 1, 0);
;   u32x4 kreg[4], vreg[4];
;   bf16x8 qn[4];
;   {
;     const int kvh = h >> 2;
;     _Pragma("unroll") for (int i = 0; i < 4; ++i) {
;       int row = lrow + 32 * i;
;       kreg[i] = *(const u32x4*)(KB + (size_t)((bl << g.lgS) + kb * 128 + row) * 256 + kvh * 128 + lcc * 8);
;       vreg[i] = *(const u32x4*)(VT + (((size_t)(bl * 2 + kvh) * 128 + row) << g.lgS) + kb * 128 + lcc * 8);
;     }
;     _Pragma("unroll") for (int ks = 0; ks < 4; ++ks)
;       qn[ks] = *(const bf16x8*)(Q + (size_t)((bl << g.lgS) + qb * 128 + qrow0 + fr) * 1024 + h * 128 + ks * 32 + fq * 8);
;   }
;   bf16x8 qf[4];
;   f32x4 o[8];
;   _Pragma("unroll") for (int ks = 0; ks < 4; ++ks) qf[ks] = qn[ks];
;   _Pragma("unroll") for (int dt = 0; dt < 8; ++dt) o[dt] = f32x4{0.f, 0.f, 0.f, 0.f};
;   float mrun = 0.f, lrun = 0.f;
.LBB0_728:
	v_readlane_b32 s58, v254, 22
	v_readlane_b32 s59, v254, 20
	v_readlane_b32 s4, v254, 3
	s_nop 3
	s_cmpk_lg_i32 s4, 0x100
	s_cbranch_scc1 .Lattn_slot_s_done
	s_lshr_b32 s4, s41, 5
	s_mul_i32 s59, s59, s4
	s_add_i32 s41, s59, s4
	s_mov_b32 s58, 1
.Lattn_slot_s_done:
	s_cmp_ge_u32 s59, s41
	s_cbranch_scc1 .LBB0_750
.LBB0_729:
	s_waitcnt lgkmcnt(0)
	s_add_u32 s6, s8, 0x17260000
	s_addc_u32 s7, s9, 0
	s_add_u32 s4, s8, 0x1f260000
	s_addc_u32 s5, s9, 0
	s_add_u32 s10, s8, 0x21260000
	s_addc_u32 s11, s9, 0
	s_add_u32 s8, s8, 0x23260000
	s_addc_u32 s9, s9, 0
	s_lshl_b32 s15, 1, s40
	s_lshr_b32 s67, s15, 7
	s_and_b64 s[12:13], s[12:13], exec
	s_cselect_b32 s12, 0, 5
	s_add_i32 s14, s14, s12
	v_readlane_b32 s0, v254, 17
	s_lshl_b32 s0, s0, s14
	s_add_i32 s13, s59, s0
	s_add_i32 s12, s40, 0xfffc
	s_lshr_b32 s12, s13, s12
	v_writelane_b32 v254, s0, 42
	s_and_b32 s65, s12, 0xffff
	s_add_i32 s0, s40, -4
	s_lshl_b32 s12, s65, s0
	s_sub_i32 s12, s13, s12
	s_add_i32 s66, s67, -1
	s_add_i32 s63, s40, -7
	s_lshr_b32 s63, s12, s63
	s_and_b32 s66, s12, s66
	s_max_i32 s12, s66, 1
	s_add_i32 s72, s12, -1
	s_lshl_b32 s13, s63, 5
	s_lshl_b32 s12, s65, s40
	s_lshl_b32 s14, s72, 7
	s_and_b32 s13, s13, 0x80
	s_lshr_b32 s62, s15, 4
	s_add_i32 s22, s14, s12
	s_lshl_b32 s14, s13, 1
	v_and_b32_e32 v37, 15, v33
	s_add_u32 s14, s4, s14
	s_addc_u32 s15, s5, 0
	v_lshlrev_b32_e32 v130, 4, v37
	v_mov_b32_e32 v131, v187
	v_lshl_add_u64 v[24:25], s[14:15], 0, v[130:131]
	s_lshl_b32 s14, s65, 8
	s_or_b32 s20, s14, s13
	s_lshl_b32 s13, s72, 8
	s_add_u32 s14, s10, s13
	v_ashrrev_i32_e32 v32, 2, v33
	s_addc_u32 s15, s11, 0
	s_lshl_b32 s13, s66, 7
	v_bfi_b32 v145, -16, v32, v33
	s_add_i32 s13, s13, s12
	v_ashrrev_i32_e32 v128, 4, v33
	v_add_u32_e32 v34, s13, v145
	v_add_u32_e32 v132, 32, v128
	v_add_u32_e32 v134, 64, v128
	v_add_u32_e32 v136, 0x60, v128
	v_ashrrev_i32_e32 v35, 31, v34
	v_add_u32_e32 v0, s22, v128
	v_ashrrev_i32_e32 v129, 31, v128
	v_add_u32_e32 v8, s22, v132
	v_ashrrev_i32_e32 v133, 31, v132
	v_add_u32_e32 v16, s22, v134
	v_ashrrev_i32_e32 v135, 31, v134
	v_add_u32_e32 v26, s22, v136
	v_ashrrev_i32_e32 v137, 31, v136
	v_lshlrev_b64 v[34:35], 11, v[34:35]
	v_ashrrev_i32_e32 v1, 31, v0
	v_lshl_add_u64 v[4:5], s[20:21], 0, v[128:129]
	v_ashrrev_i32_e32 v9, 31, v8
	v_lshl_add_u64 v[12:13], s[20:21], 0, v[132:133]
	v_ashrrev_i32_e32 v17, 31, v16
	v_lshl_add_u64 v[20:21], s[20:21], 0, v[134:135]
	v_ashrrev_i32_e32 v27, 31, v26
	v_lshl_add_u64 v[30:31], s[20:21], 0, v[136:137]
	v_lshl_add_u64 v[34:35], s[6:7], 0, v[34:35]
	s_lshl_b32 s20, s63, 8
	v_lshl_add_u64 v[28:29], s[14:15], 0, v[130:131]
	v_lshlrev_b64 v[0:1], 9, v[0:1]
	v_lshlrev_b64 v[4:5], s40, v[4:5]
	v_lshlrev_b64 v[8:9], 9, v[8:9]
	v_lshlrev_b64 v[12:13], s40, v[12:13]
	v_lshlrev_b64 v[16:17], 9, v[16:17]
	v_lshlrev_b64 v[20:21], s40, v[20:21]
	v_lshlrev_b64 v[26:27], 9, v[26:27]
	v_lshlrev_b64 v[30:31], s40, v[30:31]
	v_lshl_add_u64 v[34:35], v[34:35], 0, s[20:21]
	v_and_b32_e32 v138, 48, v33
	v_mov_b32_e32 v139, v187
	v_lshl_add_u64 v[0:1], v[24:25], 0, v[0:1]
	v_lshl_add_u64 v[4:5], v[4:5], 1, v[28:29]
	v_lshl_add_u64 v[8:9], v[24:25], 0, v[8:9]
	v_lshl_add_u64 v[12:13], v[12:13], 1, v[28:29]
	v_lshl_add_u64 v[16:17], v[24:25], 0, v[16:17]
	v_lshl_add_u64 v[20:21], v[20:21], 1, v[28:29]
	v_lshl_add_u64 v[24:25], v[24:25], 0, v[26:27]
	v_lshl_add_u64 v[28:29], v[30:31], 1, v[28:29]
	v_lshl_add_u64 v[34:35], v[34:35], 0, v[138:139]
	global_load_dwordx4 v[0:3], v[0:1], off
	v_and_b32_e32 v36, 63, v33
	global_load_dwordx4 v[4:7], v[4:5], off
	v_bfe_u32 v38, v33, 4, 2
	global_load_dwordx4 v[8:11], v[8:9], off
	v_writelane_b32 v254, s0, 44
	global_load_dwordx4 v[12:15], v[12:13], off
	v_readlane_b32 s0, v254, 40
	global_load_dwordx4 v[16:19], v[16:17], off
	v_lshl_add_u64 v[140:141], s[4:5], 0, v[130:131]
	global_load_dwordx4 v[20:23], v[20:21], off
	s_lshl_b32 s4, s0, 3
	global_load_dwordx4 v[24:27], v[24:25], off
	s_and_b32 s70, s4, 8
	global_load_dwordx4 v[28:31], v[28:29], off
	s_nop 0
	global_load_dwordx4 v[108:111], v[34:35], off
	global_load_dwordx4 v[104:107], v[34:35], off offset:64
	global_load_dwordx4 v[100:103], v[34:35], off offset:128
	global_load_dwordx4 v[96:99], v[34:35], off offset:192
	v_lshlrev_b32_e32 v34, 5, v33
	v_lshlrev_b32_e32 v33, 2, v33
	v_and_b32_e32 v165, 8, v33
	v_lshlrev_b32_e32 v33, 2, v36
	v_xor_b32_e32 v168, 64, v33
	v_xor_b32_e32 v169, 0x80, v33
	v_cvt_f32_u32_e32 v33, s62
	s_movk_i32 s4, 0x110
	v_mul_lo_u32 v170, v128, s4
	s_sub_i32 s4, 0, s62
	v_rcp_iflag_f32_e32 v33, v33
	v_lshlrev_b32_e32 v32, 3, v38
	v_and_b32_e32 v139, 32, v34
	v_lshl_add_u64 v[142:143], s[10:11], 0, v[130:131]
	v_mul_f32_e32 v33, 0x4f7ffffe, v33
	v_cvt_u32_f32_e32 v33, v33
	v_mul_u32_u24_e32 v131, 0x110, v37
	v_cmp_gt_u32_e32 vcc, 16, v36
	v_mov_b32_e32 v113, 0
	v_readfirstlane_b32 s5, v33
	s_mul_i32 s4, s4, s5
	v_lshlrev_b32_e32 v144, 2, v38
	s_mul_hi_u32 s4, s5, s4
	v_lshlrev_b32_e32 v186, 1, v32
	s_mov_b32 s60, 0
	v_and_b32_e32 v164, 0xc0, v130
	s_add_i32 s67, s67, -1
	v_cndmask_b32_e64 v166, 0, 1.0, vcc
	v_sub_u32_e32 v167, v144, v145
	s_add_i32 s0, s5, s4
	s_mov_b64 s[14:15], -1
	v_mov_b32_e32 v112, 0
	v_mov_b32_e32 v64, 0
	v_mov_b32_e32 v65, v113
	v_mov_b32_e32 v66, v113
	v_mov_b32_e32 v67, v113
	v_mov_b32_e32 v68, 0
	v_mov_b32_e32 v69, v113
	v_mov_b32_e32 v70, v113
	v_mov_b32_e32 v71, v113
	v_mov_b32_e32 v72, 0
	v_mov_b32_e32 v73, v113
	v_mov_b32_e32 v74, v113
	v_mov_b32_e32 v75, v113
	v_mov_b32_e32 v76, 0
	v_mov_b32_e32 v77, v113
	v_mov_b32_e32 v78, v113
	v_mov_b32_e32 v79, v113
	v_mov_b32_e32 v80, 0
	v_mov_b32_e32 v81, v113
	v_mov_b32_e32 v82, v113
	v_mov_b32_e32 v83, v113
	v_mov_b32_e32 v84, 0
	v_mov_b32_e32 v85, v113
	v_mov_b32_e32 v86, v113
	v_mov_b32_e32 v87, v113
	v_mov_b32_e32 v88, 0
	v_mov_b32_e32 v89, v113
	v_mov_b32_e32 v90, v113
	v_mov_b32_e32 v91, v113
	v_mov_b32_e32 v92, 0
	v_mov_b32_e32 v93, v113
	v_mov_b32_e32 v94, v113
	v_mov_b32_e32 v95, v113
	v_writelane_b32 v254, s0, 50
	s_waitcnt vmcnt(0)
	v_mov_b64_e32 v[32:33], v[108:109]
	v_mov_b64_e32 v[36:37], v[104:105]
	v_mov_b64_e32 v[40:41], v[100:101]
	v_mov_b64_e32 v[44:45], v[96:97]
	v_mov_b64_e32 v[34:35], v[110:111]
	v_mov_b64_e32 v[38:39], v[106:107]
	v_mov_b64_e32 v[42:43], v[102:103]
	v_mov_b64_e32 v[46:47], v[98:99]
	s_mov_b32 s100, -1
	s_mov_b32 s101, -1
	s_lshr_b32 s99, s63, 2
	s_lshl_b32 s98, s65, 1
	s_add_i32 s99, s99, s98
	s_lshl_b32 s99, s99, 8
	s_or_b32 s99, s99, s72
	s_bitcmp1_b32 s72, 0
	s_cselect_b32 s101, s99, s101
	s_cselect_b32 s100, s100, s99
	s_mov_b32 s98, 1
	s_branch .LBB0_731

; __device__ __forceinline__ void phase_attn(const Params& p, const Grp& g, int l) {
;     ...
;   while (true) {
;     char* Ks = g_shm + par * (256 * KPITCH); char* Vs = Ks + 128 * KPITCH;
;     par ^= 1;
;     _Pragma("unroll") for (int i = 0; i < 4; ++i) {
;       int row = lrow + 32 * i;
;       *(u32x4*)(Ks + row * KPITCH + lcc * 16) = kreg[i];
;       {
;         const int grp = lcc >> 2, c4 = lcc & 3, t = c4 >> 1, g0 = (c4 & 1) * 2;
;         char* vp = Vs + row * KPITCH + (grp * 32 + g0 * 8 + t * 4) * 2;
;         *(uint2*)(vp) = make_uint2(vreg[i][0], vreg[i][1]);
;         *(uint2*)(vp + 16) = make_uint2(vreg[i][2], vreg[i][3]);
;       }
;     }
;     const bool first_ = first;
;     _Pragma("unroll") for (int ks = 0; ks < 4; ++ks) qf[ks] = first_ ? qn[ks] : qf[ks];
;     if (first_) { mrun = p.sink[l * 8 + h] * LOG2E; lrun = (fq == 0) ? 1.f : 0.f; }
;     __syncthreads();
.LBB0_731:
	s_and_b32 s4, s72, 1
	s_mul_i32 s4, s4, 0x11000
	s_add_i32 s22, s4, 0
	s_cmp_eq_u32 s98, 0
	s_cbranch_scc1 .Lattn_nostage
	s_cmp_eq_u32 s98, 3
	s_cbranch_scc0 .Lattn_stage
	s_barrier
.Lattn_stage:
	v_add3_u32 v48, s22, v164, v139
	v_add3_u32 v49, s22, v130, v170
	ds_write_b128 v49, v[0:3]
	v_add3_u32 v0, v48, v165, v170
	v_add_u32_e32 v1, 0x8800, v0
	ds_write2_b64 v1, v[4:5], v[6:7] offset1:2
	ds_write_b128 v49, v[8:11] offset:8704
	v_add_u32_e32 v1, 0xa800, v0
	ds_write2_b64 v1, v[12:13], v[14:15] offset0:64 offset1:66
	ds_write_b128 v49, v[16:19] offset:17408
	v_add_u32_e32 v1, 0xc800, v0
	v_add_u32_e32 v0, 0xe800, v0
	ds_write2_b64 v1, v[20:21], v[22:23] offset0:128 offset1:130
	ds_write_b128 v49, v[24:27] offset:26112
	ds_write2_b64 v0, v[28:29], v[30:31] offset0:192 offset1:194
.Lattn_nostage:
	s_andn2_b64 vcc, exec, s[14:15]
	v_mov_b32_e32 v171, v113
	v_mov_b32_e32 v172, v112
	s_cbranch_vccnz .LBB0_733
	s_add_i32 s20, s63, s70
	s_lshl_b64 s[4:5], s[20:21], 2
	s_add_u32 s4, s68, s4
	s_addc_u32 s5, s69, s5
	s_load_dword s4, s[4:5], 0x0
	v_mov_b32_e32 v171, v166
	s_waitcnt lgkmcnt(0)
	v_mov_b32_e32 v0, s4
	v_mul_f32_e32 v172, 0x3fb8aa3b, v0

; __device__ __forceinline__ void phase_attn(const Params& p, const Grp& g, int l) {
;     ...
;     const int c_bl = bl, c_qb = qb, c_h = h, c_kb = kb;
;     const bool last_of_item = (c_kb == min(c_qb + 1, nqb - 1));
;     bool have_next = true;
;     if (last_of_item) {
;       slot += sstride;
;       item = xq * ipx + slot;
;       if (slot < send) { bl = __builtin_amdgcn_readfirstlane(item / (nqb * 8)); rem = item - bl * (nqb * 8); qb = rem >> 3; h = rem & 7; kb = max(qb - 1, 0); }
;       else have_next = false;
;     } else kb = kb + 1;
.LBB0_735:
	s_andn2_b64 vcc, exec, s[4:5]
	s_cbranch_vccnz .LBB0_738
	s_add_i32 s59, s59, s58
	s_mov_b64 s[12:13], 0
	s_cmp_ge_i32 s59, s41
	s_mov_b32 s73, s65
	s_mov_b32 s61, s66
	s_mov_b32 s64, s63
	s_mov_b32 s71, s72
	s_cbranch_scc1 .LBB0_739
	v_readlane_b32 s0, v254, 42
	s_add_i32 s4, s59, s0
	s_abs_i32 s12, s4
	v_readlane_b32 s0, v254, 50
	s_mul_hi_u32 s13, s12, s0
	s_mul_i32 s20, s13, s62
	s_sub_i32 s12, s12, s20
	s_ashr_i32 s5, s4, 31
	s_add_i32 s20, s13, 1
	s_sub_i32 s23, s12, s62
	s_cmp_ge_u32 s12, s62
	s_cselect_b32 s13, s20, s13
	s_cselect_b32 s12, s23, s12
	s_add_i32 s20, s13, 1
	s_cmp_ge_u32 s12, s62
	s_cselect_b32 s12, s20, s13
	s_xor_b32 s12, s12, s5
	s_sub_i32 s73, s12, s5
	v_readlane_b32 s0, v254, 44
	s_lshl_b32 s5, s73, s0
	s_sub_i32 s5, s4, s5
	s_and_b32 s61, s5, s67
	s_add_i32 s64, s40, -7
	s_lshr_b32 s64, s5, s64
	s_max_i32 s4, s61, 1
	s_add_i32 s71, s4, -1
	s_mov_b64 s[12:13], -1
	s_branch .LBB0_739

; __device__ __forceinline__ void phase_attn(const Params& p, const Grp& g, int l) {
;     ...
;     if (last_of_item) {
;       slot += sstride;
;       item = xq * ipx + slot;
;       if (slot < send) { bl = __builtin_amdgcn_readfirstlane(item / (nqb * 8)); rem = item - bl * (nqb * 8); qb = rem >> 3; h = rem & 7; kb = max(qb - 1, 0); }
;       else have_next = false;
;     } else kb = kb + 1;
;     {
;       const int kvh = h >> 2;
;       _Pragma("unroll") for (int i = 0; i < 4; ++i) {
;         int row = lrow + 32 * i;
;         kreg[i] = *(const u32x4*)(KB + (size_t)((bl << g.lgS) + kb * 128 + row) * 256 + kvh * 128 + lcc * 8);
;         vreg[i] = *(const u32x4*)(VT + (((size_t)(bl * 2 + kvh) * 128 + row) << g.lgS) + kb * 128 + lcc * 8);
;       }
;       _Pragma("unroll") for (int ks = 0; ks < 4; ++ks)
;         qn[ks] = *(const bf16x8*)(Q + (size_t)((bl << g.lgS) + qb * 128 + qrow0 + fr) * 1024 + h * 128 + ks * 32 + fq * 8);
;     }
;     u32x4 zreg[4];
;     if (last_of_item) {
;       const bf16* zp = SZA + (size_t)((c_bl << g.lgS) + c_qb * 128 + qrow0 + fr) * 1024 + c_h * 128 + fq * 4;
;       _Pragma("unroll") for (int i = 0; i < 4; ++i) {
;         uint2 a = *(const uint2*)(zp + (2 * i) * 16), b = *(const uint2*)(zp + (2 * i + 1) * 16);
;         zreg[i] = u32x4{a.x, a.y, b.x, b.y};
;       }
;     } else {
;       _Pragma("unroll") for (int i = 0; i < 4; ++i) zreg[i] = u32x4{0u, 0u, 0u, 0u};
;     }
.LBB0_739:
	s_lshr_b32 s99, s64, 2
	s_lshl_b32 s98, s73, 1
	s_add_i32 s99, s99, s98
	s_lshl_b32 s99, s99, 8
	s_or_b32 s99, s99, s71
	s_mov_b32 s98, 0
	s_bitcmp1_b32 s71, 0
	s_cbranch_scc1 .Lattn_res1
	s_cmp_eq_u32 s100, s99
	s_cbranch_scc1 .Lattn_dec_done
	s_mov_b32 s100, s99
	s_branch .Lattn_need
.Lattn_res1:
	s_cmp_eq_u32 s101, s99
	s_cbranch_scc1 .Lattn_dec_done
	s_mov_b32 s101, s99
.Lattn_need:
	s_mov_b32 s98, 1
	s_xor_b32 s99, s71, s72
	s_bitcmp1_b32 s99, 0
	s_cbranch_scc1 .Lattn_dec_done
	s_mov_b32 s98, 3
.Lattn_dec_done:
	s_lshr_b32 s5, s64, 2
	s_lshl_b32 s1, s73, 1
	s_lshl_b32 s0, s73, s40
	s_lshl_b32 s4, s71, 7
	s_or_b32 vcc_lo, s1, s5
	s_lshl_b32 s1, s61, 7
	s_add_i32 s23, s0, s4
	s_add_i32 s0, s0, s1
	v_add_u32_e32 v0, s23, v128
	v_add_u32_e32 v8, s23, v132
	v_add_u32_e32 v16, s23, v134
	v_add_u32_e32 v28, s23, v136
	v_add_u32_e32 v48, s0, v145
	s_lshl_b32 s20, s5, 8
	s_ashr_i32 vcc_hi, vcc_lo, 31
	v_ashrrev_i32_e32 v1, 31, v0
	v_ashrrev_i32_e32 v9, 31, v8
	v_ashrrev_i32_e32 v17, 31, v16
	v_ashrrev_i32_e32 v29, 31, v28
	v_ashrrev_i32_e32 v49, 31, v48
	v_lshl_add_u64 v[24:25], v[140:141], 0, s[20:21]
	s_lshl_b64 vcc, vcc, 7
	v_lshlrev_b64 v[0:1], 9, v[0:1]
	v_lshlrev_b64 v[8:9], 9, v[8:9]
	v_lshlrev_b64 v[16:17], 9, v[16:17]
	v_lshlrev_b64 v[28:29], 9, v[28:29]
	v_lshlrev_b64 v[48:49], 11, v[48:49]
	s_ashr_i32 s5, s4, 31
	v_lshl_add_u64 v[0:1], v[24:25], 0, v[0:1]
	v_lshl_add_u64 v[2:3], vcc, 0, v[128:129]
	v_lshl_add_u64 v[8:9], v[24:25], 0, v[8:9]
	v_lshl_add_u64 v[10:11], vcc, 0, v[132:133]
	v_lshl_add_u64 v[16:17], v[24:25], 0, v[16:17]
	v_lshl_add_u64 v[18:19], vcc, 0, v[134:135]
	v_lshl_add_u64 v[24:25], v[24:25], 0, v[28:29]
	v_lshl_add_u64 v[28:29], vcc, 0, v[136:137]
	v_lshl_add_u64 v[48:49], s[6:7], 0, v[48:49]
	s_lshl_b32 s20, s64, 8
	v_lshl_add_u64 v[26:27], s[4:5], 1, v[142:143]
	v_lshlrev_b64 v[2:3], s40, v[2:3]
	v_lshlrev_b64 v[10:11], s40, v[10:11]
	v_lshlrev_b64 v[18:19], s40, v[18:19]
	v_lshlrev_b64 v[28:29], s40, v[28:29]
	v_lshl_add_u64 v[48:49], v[48:49], 0, s[20:21]
	v_lshl_add_u64 v[4:5], v[2:3], 1, v[26:27]
	v_lshl_add_u64 v[12:13], v[10:11], 1, v[26:27]
	v_lshl_add_u64 v[20:21], v[18:19], 1, v[26:27]
	v_lshl_add_u64 v[28:29], v[28:29], 1, v[26:27]
	v_lshl_add_u64 v[60:61], v[48:49], 0, v[186:187]
	s_cmp_eq_u32 s98, 0
	s_cbranch_scc1 .Lattn_skip_kv
	global_load_dwordx4 v[0:3], v[0:1], off
	s_nop 0
	global_load_dwordx4 v[4:7], v[4:5], off
	s_nop 0
	global_load_dwordx4 v[8:11], v[8:9], off
	s_nop 0
	global_load_dwordx4 v[12:15], v[12:13], off
	s_nop 0
	global_load_dwordx4 v[16:19], v[16:17], off
	s_nop 0
	global_load_dwordx4 v[20:23], v[20:21], off
	s_nop 0
	global_load_dwordx4 v[24:27], v[24:25], off
	s_nop 0
	global_load_dwordx4 v[28:31], v[28:29], off
	s_nop 0
.Lattn_skip_kv:
	v_cndmask_b32_e64 v112, 0, 1, s[10:11]
	v_mov_b32_e32 v148, 0
	v_cmp_ne_u32_e64 s[4:5], 1, v112
	s_andn2_b64 vcc, exec, s[10:11]
	v_lshlrev_b32_e32 v158, 1, v144
	v_mov_b32_e32 v149, 0
	v_mov_b32_e32 v146, 0
	v_mov_b32_e32 v147, 0
	v_mov_b32_e32 v152, 0
	v_mov_b32_e32 v153, 0
	v_mov_b32_e32 v150, 0
	v_mov_b32_e32 v151, 0
	v_mov_b32_e32 v156, 0
	v_mov_b32_e32 v157, 0
	v_mov_b32_e32 v154, 0
	v_mov_b32_e32 v155, 0
	v_mov_b32_e32 v162, 0
	v_mov_b32_e32 v163, 0
	v_mov_b32_e32 v160, 0
	v_mov_b32_e32 v161, 0
	s_cbranch_vccnz .LBB0_741
	global_load_dwordx4 v[48:51], v[60:61], off
	global_load_dwordx4 v[52:55], v[60:61], off offset:64
	global_load_dwordx4 v[56:59], v[60:61], off offset:128
	s_nop 0
	global_load_dwordx4 v[60:63], v[60:61], off offset:192
	s_lshl_b32 s0, s65, s40
	s_lshl_b32 s1, s66, 7
	s_add_i32 s0, s0, s1
	v_add_u32_e32 v112, s0, v145
	v_ashrrev_i32_e32 v113, 31, v112
	v_lshlrev_b64 v[112:113], 11, v[112:113]
	v_lshl_add_u64 v[112:113], s[8:9], 0, v[112:113]
	s_lshl_b32 s20, s63, 8
	v_lshl_add_u64 v[112:113], v[112:113], 0, s[20:21]
	v_mov_b32_e32 v159, v187
	v_lshl_add_u64 v[112:113], v[112:113], 0, v[158:159]
	global_load_dwordx2 v[162:163], v[112:113], off
	global_load_dwordx2 v[160:161], v[112:113], off offset:32
	global_load_dwordx2 v[156:157], v[112:113], off offset:64
	global_load_dwordx2 v[154:155], v[112:113], off offset:96
	global_load_dwordx2 v[152:153], v[112:113], off offset:128
	global_load_dwordx2 v[150:151], v[112:113], off offset:160
	global_load_dwordx2 v[148:149], v[112:113], off offset:192
	global_load_dwordx2 v[146:147], v[112:113], off offset:224

; __global__ __launch_bounds__(512, 2) void fwd_megakernel(Params p_in) {
;   cg::grid_group grid = cg::this_grid();
;   KargPtr pp = (KargPtr)__builtin_amdgcn_kernarg_segment_ptr();
;   int step = 0;
	.amdhsa_kernel _Z14fwd_megakernel6Params
		.amdhsa_group_segment_fixed_size 0
		.amdhsa_private_segment_fixed_size 0
		.amdhsa_kernarg_size 352
		.amdhsa_user_sgpr_count 2
		.amdhsa_user_sgpr_dispatch_ptr 0
		.amdhsa_user_sgpr_queue_ptr 0
		.amdhsa_user_sgpr_kernarg_segment_ptr 1
		.amdhsa_user_sgpr_dispatch_id 0
		.amdhsa_user_sgpr_kernarg_preload_length 0
		.amdhsa_user_sgpr_kernarg_preload_offset 0
		.amdhsa_user_sgpr_private_segment_size 0
		.amdhsa_uses_dynamic_stack 0
		.amdhsa_enable_private_segment 0
		.amdhsa_system_sgpr_workgroup_id_x 1
		.amdhsa_system_sgpr_workgroup_id_y 0
		.amdhsa_system_sgpr_workgroup_id_z 0
		.amdhsa_system_sgpr_workgroup_info 0
		.amdhsa_system_vgpr_workitem_id 2
		.amdhsa_next_free_vgpr 255
		.amdhsa_next_free_sgpr 102
		.amdhsa_accum_offset 256
		.amdhsa_reserve_vcc 1
		.amdhsa_float_round_mode_32 0
		.amdhsa_float_round_mode_16_64 0
		.amdhsa_float_denorm_mode_32 3
		.amdhsa_float_denorm_mode_16_64 3
		.amdhsa_dx10_clamp 1
		.amdhsa_ieee_mode 1
		.amdhsa_fp16_overflow 0
		.amdhsa_tg_split 0
		.amdhsa_exception_fp_ieee_invalid_op 0
		.amdhsa_exception_fp_denorm_src 0
		.amdhsa_exception_fp_ieee_div_zero 0
		.amdhsa_exception_fp_ieee_overflow 0
		.amdhsa_exception_fp_ieee_underflow 0
		.amdhsa_exception_fp_ieee_inexact 0
		.amdhsa_exception_int_div_zero 0
	.end_amdhsa_kernel

; __global__ __launch_bounds__(512, 2) void fwd_megakernel(Params p_in) {
;   cg::grid_group grid = cg::this_grid();
;   KargPtr pp = (KargPtr)__builtin_amdgcn_kernarg_segment_ptr();
;   int step = 0;
amdhsa.kernels:
  - .agpr_count:     0
    .args:
      - .offset:         0
        .size:           96
        .value_kind:     by_value
      - .offset:         96
        .size:           4
        .value_kind:     hidden_block_count_x
      - .offset:         100
        .size:           4
        .value_kind:     hidden_block_count_y
      - .offset:         104
        .size:           4
        .value_kind:     hidden_block_count_z
      - .offset:         108
        .size:           2
        .value_kind:     hidden_group_size_x
      - .offset:         110
        .size:           2
        .value_kind:     hidden_group_size_y
      - .offset:         112
        .size:           2
        .value_kind:     hidden_group_size_z
      - .offset:         114
        .size:           2
        .value_kind:     hidden_remainder_x
      - .offset:         116
        .size:           2
        .value_kind:     hidden_remainder_y
      - .offset:         118
        .size:           2
        .value_kind:     hidden_remainder_z
      - .offset:         136
        .size:           8
        .value_kind:     hidden_global_offset_x
      - .offset:         144
        .size:           8
        .value_kind:     hidden_global_offset_y
      - .offset:         152
        .size:           8
        .value_kind:     hidden_global_offset_z
      - .offset:         160
        .size:           2
        .value_kind:     hidden_grid_dims
      - .offset:         184
        .size:           8
        .value_kind:     hidden_multigrid_sync_arg
      - .offset:         216
        .size:           4
        .value_kind:     hidden_dynamic_lds_size
    .group_segment_fixed_size: 0
    .kernarg_segment_align: 8
    .kernarg_segment_size: 352
    .language:       OpenCL C
    .language_version:
      - 2
      - 0
    .max_flat_workgroup_size: 512
    .name:           _Z14fwd_megakernel6Params
    .private_segment_fixed_size: 0
    .sgpr_count:     108
    .sgpr_spill_count: 101
    .symbol:         _Z14fwd_megakernel6Params.kd
    .uniform_work_group_size: 1
    .uses_dynamic_stack: false
    .vgpr_count:     255
    .vgpr_spill_count: 0
    .wavefront_size: 64
